# XCD-local barriers: L1 invalidate issued behind the arrival atomic by every workgroup (also the last arriver); no invalidate after the release
# speedup vs baseline: 1.0002x; 1.0002x over previous
; __device__ __forceinline__ int lane_now() { int l; asm volatile("v_mbcnt_lo_u32_b32 %0, -1, 0\n\tv_mbcnt_hi_u32_b32 %0, -1, %0" : "=v"(l)); return l; }
; __device__ __forceinline__ unsigned xb_ld(unsigned* p)              { return __hip_atomic_load(p, __ATOMIC_RELAXED, __HIP_MEMORY_SCOPE_AGENT); }
; __device__ __forceinline__ unsigned xb_add(unsigned* p, unsigned v) { return __hip_atomic_fetch_add(p, v, __ATOMIC_RELAXED, __HIP_MEMORY_SCOPE_AGENT); }
; #define XB_SPIN(cond, bar) do { unsigned _sp = 0; while (cond) { __builtin_amdgcn_s_sleep(1); \
;     if ((++_sp & 255u) == 0u) { if (xb_ld(&(bar)[XB_TMO])) break; if (_sp > XB_SPIN_CAP) { atomicAdd(&(bar)[XB_TMO], 1u); break; } } } } while (0)
; __device__ __forceinline__ void xcd_barrier(const XcdBarrier& b) {
;     asm volatile("s_waitcnt vmcnt(0)" ::: "memory");
;     __syncthreads();
;     if (b.w0 && lane_now() == 0) {
;         unsigned* bar = b.bar;
;         __builtin_amdgcn_s_waitcnt(0);
;         unsigned nloc = b.st[0], nx = b.st[1];
;         if (nloc == 0u) { xcd_barrier_complete(bar, b.x, nloc, nx); b.st[0] = nloc; b.st[1] = nx; }
;         const unsigned old = xb_add(&bar[XB_XSUB(b.x)], 1u);
;         const unsigned gen = old / nloc;
;         if (old + 1u == (gen + 1u) * nloc) {
;             __builtin_amdgcn_fence(__ATOMIC_RELEASE, "agent");
;             asm volatile("s_waitcnt vmcnt(0)" ::: "memory");
;             const unsigned og = xb_add(&bar[XB_TOP], 1u);
;             const unsigned tg = og / nx;
;             if (og + 1u == (tg + 1u) * nx) xb_add(&bar[XB_TOPGEN], 1u);
;             else XB_SPIN(xb_ld(&bar[XB_TOPGEN]) == tg, bar);
;             __builtin_amdgcn_fence(__ATOMIC_ACQUIRE, "agent");
;             xb_add(&bar[XB_XGEN(b.x)], 1u);
;             asm volatile("s_waitcnt vmcnt(0)" ::: "memory");
;         } else {
;             XB_SPIN(xb_ld(&bar[XB_XGEN(b.x)]) == gen, bar);
;             __builtin_amdgcn_fence(__ATOMIC_ACQUIRE, "agent");
;             asm volatile("s_waitcnt vmcnt(0)" ::: "memory");
;         }
;     }
;     __syncthreads();
.LBB0_106:
	s_or_b64 exec, exec, s[10:11]
	v_cvt_f32_u32_e32 v4, v2
	v_readlane_b32 s100, v244, 61
	s_cmp_eq_u32 s100, 0
	s_cbranch_scc1 .Lel_a1
	buffer_inv sc1
	s_waitcnt vmcnt(1)
	s_branch .Lel_c1

; __device__ __forceinline__ int lane_now() { int l; asm volatile("v_mbcnt_lo_u32_b32 %0, -1, 0\n\tv_mbcnt_hi_u32_b32 %0, -1, %0" : "=v"(l)); return l; }
; __device__ __forceinline__ unsigned xb_ld(unsigned* p)              { return __hip_atomic_load(p, __ATOMIC_RELAXED, __HIP_MEMORY_SCOPE_AGENT); }
; __device__ __forceinline__ unsigned xb_add(unsigned* p, unsigned v) { return __hip_atomic_fetch_add(p, v, __ATOMIC_RELAXED, __HIP_MEMORY_SCOPE_AGENT); }
; #define XB_SPIN(cond, bar) do { unsigned _sp = 0; while (cond) { __builtin_amdgcn_s_sleep(1); \
;     if ((++_sp & 255u) == 0u) { if (xb_ld(&(bar)[XB_TMO])) break; if (_sp > XB_SPIN_CAP) { atomicAdd(&(bar)[XB_TMO], 1u); break; } } } } while (0)
; __device__ __forceinline__ void xcd_barrier(const XcdBarrier& b) {
;     asm volatile("s_waitcnt vmcnt(0)" ::: "memory");
;     __syncthreads();
;     if (b.w0 && lane_now() == 0) {
;         unsigned* bar = b.bar;
;         __builtin_amdgcn_s_waitcnt(0);
;         unsigned nloc = b.st[0], nx = b.st[1];
;         if (nloc == 0u) { xcd_barrier_complete(bar, b.x, nloc, nx); b.st[0] = nloc; b.st[1] = nx; }
;         const unsigned old = xb_add(&bar[XB_XSUB(b.x)], 1u);
;         const unsigned gen = old / nloc;
;         if (old + 1u == (gen + 1u) * nloc) {
;             __builtin_amdgcn_fence(__ATOMIC_RELEASE, "agent");
;             asm volatile("s_waitcnt vmcnt(0)" ::: "memory");
;             const unsigned og = xb_add(&bar[XB_TOP], 1u);
;             const unsigned tg = og / nx;
;             if (og + 1u == (tg + 1u) * nx) xb_add(&bar[XB_TOPGEN], 1u);
;             else XB_SPIN(xb_ld(&bar[XB_TOPGEN]) == tg, bar);
;             __builtin_amdgcn_fence(__ATOMIC_ACQUIRE, "agent");
;             xb_add(&bar[XB_XGEN(b.x)], 1u);
;             asm volatile("s_waitcnt vmcnt(0)" ::: "memory");
;         } else {
;             XB_SPIN(xb_ld(&bar[XB_XGEN(b.x)]) == gen, bar);
;             __builtin_amdgcn_fence(__ATOMIC_ACQUIRE, "agent");
;             asm volatile("s_waitcnt vmcnt(0)" ::: "memory");
;         }
;     }
;     __syncthreads();
.Lel_c1:
	v_readfirstlane_b32 s6, v3
	v_sub_u32_e32 v3, 0, v2
	v_rcp_iflag_f32_e32 v4, v4
	v_add_u32_e32 v5, s6, v1
	v_mul_f32_e32 v4, 0x4f7ffffe, v4
	v_cvt_u32_f32_e32 v4, v4
	v_mul_lo_u32 v1, v3, v4
	v_mul_hi_u32 v1, v4, v1
	v_add_u32_e32 v1, v4, v1
	v_mul_hi_u32 v1, v5, v1
	v_mul_lo_u32 v3, v1, v2
	v_sub_u32_e32 v3, v5, v3
	v_add_u32_e32 v4, 1, v1
	v_cmp_ge_u32_e32 vcc, v3, v2
	s_nop 1
	v_cndmask_b32_e32 v1, v1, v4, vcc
	v_sub_u32_e32 v4, v3, v2
	v_cndmask_b32_e32 v3, v3, v4, vcc
	v_add_u32_e32 v4, 1, v1
	v_cmp_ge_u32_e32 vcc, v3, v2
	v_add_u32_e32 v3, 1, v5
	s_nop 0
	v_cndmask_b32_e32 v1, v1, v4, vcc
	v_mul_lo_u32 v4, v2, v1
	v_add_u32_e32 v2, v4, v2
	v_cmp_ne_u32_e32 vcc, v3, v2
	s_and_saveexec_b64 s[6:7], vcc
	s_xor_b64 s[6:7], exec, s[6:7]
	s_cbranch_execz .LBB0_120
	s_waitcnt lgkmcnt(0)
	v_mov_b32_e32 v0, 0x2000
	global_load_dword v0, v0, s[4:5] offset:1024 sc1
	s_add_u32 s20, s4, 0x2400
	s_addc_u32 s21, s5, 0
	s_waitcnt vmcnt(0)
	v_cmp_eq_u32_e32 vcc, v0, v1
	s_and_saveexec_b64 s[10:11], vcc
	s_cbranch_execz .LBB0_119
	s_add_u32 s16, s92, 0xc0200
	s_addc_u32 s17, s93, 0
	s_mov_b32 s33, 1
	s_mov_b64 s[22:23], 0
	v_mov_b32_e32 v0, 0
	s_branch .LBB0_110

; __device__ __forceinline__ int lane_now() { int l; asm volatile("v_mbcnt_lo_u32_b32 %0, -1, 0\n\tv_mbcnt_hi_u32_b32 %0, -1, %0" : "=v"(l)); return l; }
; __device__ __forceinline__ unsigned xb_ld(unsigned* p)              { return __hip_atomic_load(p, __ATOMIC_RELAXED, __HIP_MEMORY_SCOPE_AGENT); }
; __device__ __forceinline__ unsigned xb_add(unsigned* p, unsigned v) { return __hip_atomic_fetch_add(p, v, __ATOMIC_RELAXED, __HIP_MEMORY_SCOPE_AGENT); }
; #define XB_SPIN(cond, bar) do { unsigned _sp = 0; while (cond) { __builtin_amdgcn_s_sleep(1); \
;     if ((++_sp & 255u) == 0u) { if (xb_ld(&(bar)[XB_TMO])) break; if (_sp > XB_SPIN_CAP) { atomicAdd(&(bar)[XB_TMO], 1u); break; } } } } while (0)
; __device__ __forceinline__ void xcd_barrier(const XcdBarrier& b) {
;     asm volatile("s_waitcnt vmcnt(0)" ::: "memory");
;     __syncthreads();
;     if (b.w0 && lane_now() == 0) {
;         unsigned* bar = b.bar;
;         __builtin_amdgcn_s_waitcnt(0);
;         unsigned nloc = b.st[0], nx = b.st[1];
;         if (nloc == 0u) { xcd_barrier_complete(bar, b.x, nloc, nx); b.st[0] = nloc; b.st[1] = nx; }
;         const unsigned old = xb_add(&bar[XB_XSUB(b.x)], 1u);
;         const unsigned gen = old / nloc;
;         if (old + 1u == (gen + 1u) * nloc) {
;             __builtin_amdgcn_fence(__ATOMIC_RELEASE, "agent");
;             asm volatile("s_waitcnt vmcnt(0)" ::: "memory");
;             const unsigned og = xb_add(&bar[XB_TOP], 1u);
;             const unsigned tg = og / nx;
;             if (og + 1u == (tg + 1u) * nx) xb_add(&bar[XB_TOPGEN], 1u);
;             else XB_SPIN(xb_ld(&bar[XB_TOPGEN]) == tg, bar);
;             __builtin_amdgcn_fence(__ATOMIC_ACQUIRE, "agent");
;             xb_add(&bar[XB_XGEN(b.x)], 1u);
;             asm volatile("s_waitcnt vmcnt(0)" ::: "memory");
;         } else {
;             XB_SPIN(xb_ld(&bar[XB_XGEN(b.x)]) == gen, bar);
;             __builtin_amdgcn_fence(__ATOMIC_ACQUIRE, "agent");
;             asm volatile("s_waitcnt vmcnt(0)" ::: "memory");
;         }
;     }
;     __syncthreads();
.LBB0_139:
	s_or_b64 exec, exec, s[10:11]
	s_waitcnt vmcnt(0)
	s_branch .LBB0_140
.Lel_rel1:
	v_mov_b32_e32 v0, 0x2000
	v_mov_b32_e32 v1, 1
	global_atomic_add v0, v1, s[4:5] offset:1024
	s_waitcnt vmcnt(0)
	s_branch .LBB0_140

; __device__ __forceinline__ int lane_now() { int l; asm volatile("v_mbcnt_lo_u32_b32 %0, -1, 0\n\tv_mbcnt_hi_u32_b32 %0, -1, %0" : "=v"(l)); return l; }
; __device__ __forceinline__ unsigned xb_ld(unsigned* p)              { return __hip_atomic_load(p, __ATOMIC_RELAXED, __HIP_MEMORY_SCOPE_AGENT); }
; __device__ __forceinline__ unsigned xb_add(unsigned* p, unsigned v) { return __hip_atomic_fetch_add(p, v, __ATOMIC_RELAXED, __HIP_MEMORY_SCOPE_AGENT); }
; #define XB_SPIN(cond, bar) do { unsigned _sp = 0; while (cond) { __builtin_amdgcn_s_sleep(1); \
;     if ((++_sp & 255u) == 0u) { if (xb_ld(&(bar)[XB_TMO])) break; if (_sp > XB_SPIN_CAP) { atomicAdd(&(bar)[XB_TMO], 1u); break; } } } } while (0)
; __device__ __forceinline__ void xcd_barrier(const XcdBarrier& b) {
;     asm volatile("s_waitcnt vmcnt(0)" ::: "memory");
;     __syncthreads();
;     if (b.w0 && lane_now() == 0) {
;         unsigned* bar = b.bar;
;         __builtin_amdgcn_s_waitcnt(0);
;         unsigned nloc = b.st[0], nx = b.st[1];
;         if (nloc == 0u) { xcd_barrier_complete(bar, b.x, nloc, nx); b.st[0] = nloc; b.st[1] = nx; }
;         const unsigned old = xb_add(&bar[XB_XSUB(b.x)], 1u);
;         const unsigned gen = old / nloc;
;         if (old + 1u == (gen + 1u) * nloc) {
;             __builtin_amdgcn_fence(__ATOMIC_RELEASE, "agent");
;             asm volatile("s_waitcnt vmcnt(0)" ::: "memory");
;             const unsigned og = xb_add(&bar[XB_TOP], 1u);
;             const unsigned tg = og / nx;
;             if (og + 1u == (tg + 1u) * nx) xb_add(&bar[XB_TOPGEN], 1u);
;             else XB_SPIN(xb_ld(&bar[XB_TOPGEN]) == tg, bar);
;             __builtin_amdgcn_fence(__ATOMIC_ACQUIRE, "agent");
;             xb_add(&bar[XB_XGEN(b.x)], 1u);
;             asm volatile("s_waitcnt vmcnt(0)" ::: "memory");
;         } else {
;             XB_SPIN(xb_ld(&bar[XB_XGEN(b.x)]) == gen, bar);
;             __builtin_amdgcn_fence(__ATOMIC_ACQUIRE, "agent");
;             asm volatile("s_waitcnt vmcnt(0)" ::: "memory");
;         }
;     }
;     __syncthreads();
.LBB0_176:
	s_or_b64 exec, exec, s[16:17]
	v_cvt_f32_u32_e32 v4, v2
	v_readlane_b32 s100, v244, 61
	s_cmp_eq_u32 s100, 0
	s_cbranch_scc1 .Lel_a2
	buffer_inv sc1
	s_waitcnt vmcnt(1)
	s_branch .Lel_c2

; __device__ __forceinline__ int lane_now() { int l; asm volatile("v_mbcnt_lo_u32_b32 %0, -1, 0\n\tv_mbcnt_hi_u32_b32 %0, -1, %0" : "=v"(l)); return l; }
; __device__ __forceinline__ unsigned xb_ld(unsigned* p)              { return __hip_atomic_load(p, __ATOMIC_RELAXED, __HIP_MEMORY_SCOPE_AGENT); }
; __device__ __forceinline__ unsigned xb_add(unsigned* p, unsigned v) { return __hip_atomic_fetch_add(p, v, __ATOMIC_RELAXED, __HIP_MEMORY_SCOPE_AGENT); }
; #define XB_SPIN(cond, bar) do { unsigned _sp = 0; while (cond) { __builtin_amdgcn_s_sleep(1); \
;     if ((++_sp & 255u) == 0u) { if (xb_ld(&(bar)[XB_TMO])) break; if (_sp > XB_SPIN_CAP) { atomicAdd(&(bar)[XB_TMO], 1u); break; } } } } while (0)
; __device__ __forceinline__ void xcd_barrier(const XcdBarrier& b) {
;     asm volatile("s_waitcnt vmcnt(0)" ::: "memory");
;     __syncthreads();
;     if (b.w0 && lane_now() == 0) {
;         unsigned* bar = b.bar;
;         __builtin_amdgcn_s_waitcnt(0);
;         unsigned nloc = b.st[0], nx = b.st[1];
;         if (nloc == 0u) { xcd_barrier_complete(bar, b.x, nloc, nx); b.st[0] = nloc; b.st[1] = nx; }
;         const unsigned old = xb_add(&bar[XB_XSUB(b.x)], 1u);
;         const unsigned gen = old / nloc;
;         if (old + 1u == (gen + 1u) * nloc) {
;             __builtin_amdgcn_fence(__ATOMIC_RELEASE, "agent");
;             asm volatile("s_waitcnt vmcnt(0)" ::: "memory");
;             const unsigned og = xb_add(&bar[XB_TOP], 1u);
;             const unsigned tg = og / nx;
;             if (og + 1u == (tg + 1u) * nx) xb_add(&bar[XB_TOPGEN], 1u);
;             else XB_SPIN(xb_ld(&bar[XB_TOPGEN]) == tg, bar);
;             __builtin_amdgcn_fence(__ATOMIC_ACQUIRE, "agent");
;             xb_add(&bar[XB_XGEN(b.x)], 1u);
;             asm volatile("s_waitcnt vmcnt(0)" ::: "memory");
;         } else {
;             XB_SPIN(xb_ld(&bar[XB_XGEN(b.x)]) == gen, bar);
;             __builtin_amdgcn_fence(__ATOMIC_ACQUIRE, "agent");
;             asm volatile("s_waitcnt vmcnt(0)" ::: "memory");
;         }
;     }
;     __syncthreads();
.Lel_c2:
	v_readfirstlane_b32 s10, v3
	v_sub_u32_e32 v3, 0, v2
	v_rcp_iflag_f32_e32 v4, v4
	v_add_u32_e32 v5, s10, v1
	v_mul_f32_e32 v4, 0x4f7ffffe, v4
	v_cvt_u32_f32_e32 v4, v4
	v_mul_lo_u32 v1, v3, v4
	v_mul_hi_u32 v1, v4, v1
	v_add_u32_e32 v1, v4, v1
	v_mul_hi_u32 v1, v5, v1
	v_mul_lo_u32 v3, v1, v2
	v_sub_u32_e32 v3, v5, v3
	v_add_u32_e32 v4, 1, v1
	v_cmp_ge_u32_e32 vcc, v3, v2
	s_nop 1
	v_cndmask_b32_e32 v1, v1, v4, vcc
	v_sub_u32_e32 v4, v3, v2
	v_cndmask_b32_e32 v3, v3, v4, vcc
	v_add_u32_e32 v4, 1, v1
	v_cmp_ge_u32_e32 vcc, v3, v2
	v_add_u32_e32 v3, 1, v5
	s_nop 0
	v_cndmask_b32_e32 v1, v1, v4, vcc
	v_mul_lo_u32 v4, v2, v1
	v_add_u32_e32 v2, v4, v2
	v_cmp_ne_u32_e32 vcc, v3, v2
	s_and_saveexec_b64 s[10:11], vcc
	s_xor_b64 s[10:11], exec, s[10:11]
	s_cbranch_execz .LBB0_190
	s_waitcnt lgkmcnt(0)
	v_mov_b32_e32 v0, 0x2000
	global_load_dword v0, v0, s[6:7] offset:1024 sc1
	s_add_u32 s22, s6, 0x2400
	s_addc_u32 s23, s7, 0
	s_waitcnt vmcnt(0)
	v_cmp_eq_u32_e32 vcc, v0, v1
	s_and_saveexec_b64 s[16:17], vcc
	s_cbranch_execz .LBB0_189
	s_add_u32 s20, s92, 0xc0200
	s_addc_u32 s21, s93, 0
	s_mov_b32 s38, 1
	s_mov_b64 s[24:25], 0
	v_mov_b32_e32 v0, 0
	s_branch .LBB0_180

; __device__ __forceinline__ int lane_now() { int l; asm volatile("v_mbcnt_lo_u32_b32 %0, -1, 0\n\tv_mbcnt_hi_u32_b32 %0, -1, %0" : "=v"(l)); return l; }
; __device__ __forceinline__ unsigned xb_ld(unsigned* p)              { return __hip_atomic_load(p, __ATOMIC_RELAXED, __HIP_MEMORY_SCOPE_AGENT); }
; __device__ __forceinline__ unsigned xb_add(unsigned* p, unsigned v) { return __hip_atomic_fetch_add(p, v, __ATOMIC_RELAXED, __HIP_MEMORY_SCOPE_AGENT); }
; #define XB_SPIN(cond, bar) do { unsigned _sp = 0; while (cond) { __builtin_amdgcn_s_sleep(1); \
;     if ((++_sp & 255u) == 0u) { if (xb_ld(&(bar)[XB_TMO])) break; if (_sp > XB_SPIN_CAP) { atomicAdd(&(bar)[XB_TMO], 1u); break; } } } } while (0)
; __device__ __forceinline__ void xcd_barrier(const XcdBarrier& b) {
;     asm volatile("s_waitcnt vmcnt(0)" ::: "memory");
;     __syncthreads();
;     if (b.w0 && lane_now() == 0) {
;         unsigned* bar = b.bar;
;         __builtin_amdgcn_s_waitcnt(0);
;         unsigned nloc = b.st[0], nx = b.st[1];
;         if (nloc == 0u) { xcd_barrier_complete(bar, b.x, nloc, nx); b.st[0] = nloc; b.st[1] = nx; }
;         const unsigned old = xb_add(&bar[XB_XSUB(b.x)], 1u);
;         const unsigned gen = old / nloc;
;         if (old + 1u == (gen + 1u) * nloc) {
;             __builtin_amdgcn_fence(__ATOMIC_RELEASE, "agent");
;             asm volatile("s_waitcnt vmcnt(0)" ::: "memory");
;             const unsigned og = xb_add(&bar[XB_TOP], 1u);
;             const unsigned tg = og / nx;
;             if (og + 1u == (tg + 1u) * nx) xb_add(&bar[XB_TOPGEN], 1u);
;             else XB_SPIN(xb_ld(&bar[XB_TOPGEN]) == tg, bar);
;             __builtin_amdgcn_fence(__ATOMIC_ACQUIRE, "agent");
;             xb_add(&bar[XB_XGEN(b.x)], 1u);
;             asm volatile("s_waitcnt vmcnt(0)" ::: "memory");
;         } else {
;             XB_SPIN(xb_ld(&bar[XB_XGEN(b.x)]) == gen, bar);
;             __builtin_amdgcn_fence(__ATOMIC_ACQUIRE, "agent");
;             asm volatile("s_waitcnt vmcnt(0)" ::: "memory");
;         }
;     }
;     __syncthreads();
.LBB0_209:
	s_or_b64 exec, exec, s[16:17]
	s_waitcnt vmcnt(0)
	s_branch .LBB0_210
.Lel_rel2:
	v_mov_b32_e32 v0, 0x2000
	v_mov_b32_e32 v1, 1
	global_atomic_add v0, v1, s[6:7] offset:1024
	s_waitcnt vmcnt(0)
	s_branch .LBB0_210

; __device__ __forceinline__ int lane_now() { int l; asm volatile("v_mbcnt_lo_u32_b32 %0, -1, 0\n\tv_mbcnt_hi_u32_b32 %0, -1, %0" : "=v"(l)); return l; }
; __device__ __forceinline__ unsigned xb_ld(unsigned* p)              { return __hip_atomic_load(p, __ATOMIC_RELAXED, __HIP_MEMORY_SCOPE_AGENT); }
; __device__ __forceinline__ unsigned xb_add(unsigned* p, unsigned v) { return __hip_atomic_fetch_add(p, v, __ATOMIC_RELAXED, __HIP_MEMORY_SCOPE_AGENT); }
; #define XB_SPIN(cond, bar) do { unsigned _sp = 0; while (cond) { __builtin_amdgcn_s_sleep(1); \
;     if ((++_sp & 255u) == 0u) { if (xb_ld(&(bar)[XB_TMO])) break; if (_sp > XB_SPIN_CAP) { atomicAdd(&(bar)[XB_TMO], 1u); break; } } } } while (0)
; __device__ __forceinline__ void xcd_barrier(const XcdBarrier& b) {
;     asm volatile("s_waitcnt vmcnt(0)" ::: "memory");
;     __syncthreads();
;     if (b.w0 && lane_now() == 0) {
;         unsigned* bar = b.bar;
;         __builtin_amdgcn_s_waitcnt(0);
;         unsigned nloc = b.st[0], nx = b.st[1];
;         if (nloc == 0u) { xcd_barrier_complete(bar, b.x, nloc, nx); b.st[0] = nloc; b.st[1] = nx; }
;         const unsigned old = xb_add(&bar[XB_XSUB(b.x)], 1u);
;         const unsigned gen = old / nloc;
;         if (old + 1u == (gen + 1u) * nloc) {
;             __builtin_amdgcn_fence(__ATOMIC_RELEASE, "agent");
;             asm volatile("s_waitcnt vmcnt(0)" ::: "memory");
;             const unsigned og = xb_add(&bar[XB_TOP], 1u);
;             const unsigned tg = og / nx;
;             if (og + 1u == (tg + 1u) * nx) xb_add(&bar[XB_TOPGEN], 1u);
;             else XB_SPIN(xb_ld(&bar[XB_TOPGEN]) == tg, bar);
;             __builtin_amdgcn_fence(__ATOMIC_ACQUIRE, "agent");
;             xb_add(&bar[XB_XGEN(b.x)], 1u);
;             asm volatile("s_waitcnt vmcnt(0)" ::: "memory");
;         } else {
;             XB_SPIN(xb_ld(&bar[XB_XGEN(b.x)]) == gen, bar);
;             __builtin_amdgcn_fence(__ATOMIC_ACQUIRE, "agent");
;             asm volatile("s_waitcnt vmcnt(0)" ::: "memory");
;         }
;     }
;     __syncthreads();
.Lel_c3:
	v_readfirstlane_b32 s10, v3
	v_sub_u32_e32 v3, 0, v2
	v_rcp_iflag_f32_e32 v4, v4
	v_add_u32_e32 v5, s10, v1
	v_mul_f32_e32 v4, 0x4f7ffffe, v4
	v_cvt_u32_f32_e32 v4, v4
	v_mul_lo_u32 v1, v3, v4
	v_mul_hi_u32 v1, v4, v1
	v_add_u32_e32 v1, v4, v1
	v_mul_hi_u32 v1, v5, v1
	v_mul_lo_u32 v3, v1, v2
	v_sub_u32_e32 v3, v5, v3
	v_add_u32_e32 v4, 1, v1
	v_cmp_ge_u32_e32 vcc, v3, v2
	s_nop 1
	v_cndmask_b32_e32 v1, v1, v4, vcc
	v_sub_u32_e32 v4, v3, v2
	v_cndmask_b32_e32 v3, v3, v4, vcc
	v_add_u32_e32 v4, 1, v1
	v_cmp_ge_u32_e32 vcc, v3, v2
	v_add_u32_e32 v3, 1, v5
	s_nop 0
	v_cndmask_b32_e32 v1, v1, v4, vcc
	v_mul_lo_u32 v4, v2, v1
	v_add_u32_e32 v2, v4, v2
	v_cmp_ne_u32_e32 vcc, v3, v2
	s_and_saveexec_b64 s[10:11], vcc
	s_xor_b64 s[10:11], exec, s[10:11]
	s_cbranch_execz .LBB0_272
	s_waitcnt lgkmcnt(0)
	v_mov_b32_e32 v0, 0x2000
	global_load_dword v0, v0, s[6:7] offset:1024 sc1
	s_add_u32 s22, s6, 0x2400
	s_addc_u32 s23, s7, 0
	s_waitcnt vmcnt(0)
	v_cmp_eq_u32_e32 vcc, v0, v1
	s_and_saveexec_b64 s[16:17], vcc
	s_cbranch_execz .LBB0_271
	s_add_u32 s20, s92, 0xc0200
	s_addc_u32 s21, s93, 0
	s_mov_b32 s36, 1
	s_mov_b64 s[24:25], 0
	v_mov_b32_e32 v0, 0
	s_branch .LBB0_262

; __device__ __forceinline__ int lane_now() { int l; asm volatile("v_mbcnt_lo_u32_b32 %0, -1, 0\n\tv_mbcnt_hi_u32_b32 %0, -1, %0" : "=v"(l)); return l; }
; __device__ __forceinline__ unsigned xb_ld(unsigned* p)              { return __hip_atomic_load(p, __ATOMIC_RELAXED, __HIP_MEMORY_SCOPE_AGENT); }
; __device__ __forceinline__ unsigned xb_add(unsigned* p, unsigned v) { return __hip_atomic_fetch_add(p, v, __ATOMIC_RELAXED, __HIP_MEMORY_SCOPE_AGENT); }
; #define XB_SPIN(cond, bar) do { unsigned _sp = 0; while (cond) { __builtin_amdgcn_s_sleep(1); \
;     if ((++_sp & 255u) == 0u) { if (xb_ld(&(bar)[XB_TMO])) break; if (_sp > XB_SPIN_CAP) { atomicAdd(&(bar)[XB_TMO], 1u); break; } } } } while (0)
; __device__ __forceinline__ void xcd_barrier(const XcdBarrier& b) {
;     asm volatile("s_waitcnt vmcnt(0)" ::: "memory");
;     __syncthreads();
;     if (b.w0 && lane_now() == 0) {
;         unsigned* bar = b.bar;
;         __builtin_amdgcn_s_waitcnt(0);
;         unsigned nloc = b.st[0], nx = b.st[1];
;         if (nloc == 0u) { xcd_barrier_complete(bar, b.x, nloc, nx); b.st[0] = nloc; b.st[1] = nx; }
;         const unsigned old = xb_add(&bar[XB_XSUB(b.x)], 1u);
;         const unsigned gen = old / nloc;
;         if (old + 1u == (gen + 1u) * nloc) {
;             __builtin_amdgcn_fence(__ATOMIC_RELEASE, "agent");
;             asm volatile("s_waitcnt vmcnt(0)" ::: "memory");
;             const unsigned og = xb_add(&bar[XB_TOP], 1u);
;             const unsigned tg = og / nx;
;             if (og + 1u == (tg + 1u) * nx) xb_add(&bar[XB_TOPGEN], 1u);
;             else XB_SPIN(xb_ld(&bar[XB_TOPGEN]) == tg, bar);
;             __builtin_amdgcn_fence(__ATOMIC_ACQUIRE, "agent");
;             xb_add(&bar[XB_XGEN(b.x)], 1u);
;             asm volatile("s_waitcnt vmcnt(0)" ::: "memory");
;         } else {
;             XB_SPIN(xb_ld(&bar[XB_XGEN(b.x)]) == gen, bar);
;             __builtin_amdgcn_fence(__ATOMIC_ACQUIRE, "agent");
;             asm volatile("s_waitcnt vmcnt(0)" ::: "memory");
;         }
;     }
;     __syncthreads();
.LBB0_1118:
	s_or_b64 exec, exec, s[8:9]
	v_cvt_f32_u32_e32 v4, v2
	v_readlane_b32 s100, v244, 61
	s_cmp_eq_u32 s100, 0
	s_cbranch_scc1 .Lel_a9
	buffer_inv sc1
	s_waitcnt vmcnt(1)
	s_branch .Lel_c9

; __device__ __forceinline__ int lane_now() { int l; asm volatile("v_mbcnt_lo_u32_b32 %0, -1, 0\n\tv_mbcnt_hi_u32_b32 %0, -1, %0" : "=v"(l)); return l; }
; __device__ __forceinline__ unsigned xb_ld(unsigned* p)              { return __hip_atomic_load(p, __ATOMIC_RELAXED, __HIP_MEMORY_SCOPE_AGENT); }
; __device__ __forceinline__ unsigned xb_add(unsigned* p, unsigned v) { return __hip_atomic_fetch_add(p, v, __ATOMIC_RELAXED, __HIP_MEMORY_SCOPE_AGENT); }
; #define XB_SPIN(cond, bar) do { unsigned _sp = 0; while (cond) { __builtin_amdgcn_s_sleep(1); \
;     if ((++_sp & 255u) == 0u) { if (xb_ld(&(bar)[XB_TMO])) break; if (_sp > XB_SPIN_CAP) { atomicAdd(&(bar)[XB_TMO], 1u); break; } } } } while (0)
; __device__ __forceinline__ void xcd_barrier(const XcdBarrier& b) {
;     asm volatile("s_waitcnt vmcnt(0)" ::: "memory");
;     __syncthreads();
;     if (b.w0 && lane_now() == 0) {
;         unsigned* bar = b.bar;
;         __builtin_amdgcn_s_waitcnt(0);
;         unsigned nloc = b.st[0], nx = b.st[1];
;         if (nloc == 0u) { xcd_barrier_complete(bar, b.x, nloc, nx); b.st[0] = nloc; b.st[1] = nx; }
;         const unsigned old = xb_add(&bar[XB_XSUB(b.x)], 1u);
;         const unsigned gen = old / nloc;
;         if (old + 1u == (gen + 1u) * nloc) {
;             __builtin_amdgcn_fence(__ATOMIC_RELEASE, "agent");
;             asm volatile("s_waitcnt vmcnt(0)" ::: "memory");
;             const unsigned og = xb_add(&bar[XB_TOP], 1u);
;             const unsigned tg = og / nx;
;             if (og + 1u == (tg + 1u) * nx) xb_add(&bar[XB_TOPGEN], 1u);
;             else XB_SPIN(xb_ld(&bar[XB_TOPGEN]) == tg, bar);
;             __builtin_amdgcn_fence(__ATOMIC_ACQUIRE, "agent");
;             xb_add(&bar[XB_XGEN(b.x)], 1u);
;             asm volatile("s_waitcnt vmcnt(0)" ::: "memory");
;         } else {
;             XB_SPIN(xb_ld(&bar[XB_XGEN(b.x)]) == gen, bar);
;             __builtin_amdgcn_fence(__ATOMIC_ACQUIRE, "agent");
;             asm volatile("s_waitcnt vmcnt(0)" ::: "memory");
;         }
;     }
;     __syncthreads();
.Lel_c9:
	v_readfirstlane_b32 s6, v3
	v_sub_u32_e32 v3, 0, v2
	v_rcp_iflag_f32_e32 v4, v4
	v_add_u32_e32 v5, s6, v1
	v_mul_f32_e32 v4, 0x4f7ffffe, v4
	v_cvt_u32_f32_e32 v4, v4
	v_mul_lo_u32 v1, v3, v4
	v_mul_hi_u32 v1, v4, v1
	v_add_u32_e32 v1, v4, v1
	v_mul_hi_u32 v1, v5, v1
	v_mul_lo_u32 v3, v1, v2
	v_sub_u32_e32 v3, v5, v3
	v_add_u32_e32 v4, 1, v1
	v_cmp_ge_u32_e32 vcc, v3, v2
	s_nop 1
	v_cndmask_b32_e32 v1, v1, v4, vcc
	v_sub_u32_e32 v4, v3, v2
	v_cndmask_b32_e32 v3, v3, v4, vcc
	v_add_u32_e32 v4, 1, v1
	v_cmp_ge_u32_e32 vcc, v3, v2
	v_add_u32_e32 v3, 1, v5
	s_nop 0
	v_cndmask_b32_e32 v1, v1, v4, vcc
	v_mul_lo_u32 v4, v2, v1
	v_add_u32_e32 v2, v4, v2
	v_cmp_ne_u32_e32 vcc, v3, v2
	s_and_saveexec_b64 s[6:7], vcc
	s_xor_b64 s[6:7], exec, s[6:7]
	s_cbranch_execz .LBB0_1132
	s_waitcnt lgkmcnt(0)
	v_mov_b32_e32 v0, 0x2000
	global_load_dword v0, v0, s[4:5] offset:1024 sc1
	s_add_u32 s12, s4, 0x2400
	s_addc_u32 s13, s5, 0
	s_waitcnt vmcnt(0)
	v_cmp_eq_u32_e32 vcc, v0, v1
	s_and_saveexec_b64 s[8:9], vcc
	s_cbranch_execz .LBB0_1131
	s_add_u32 s10, s92, 0xc0200
	s_addc_u32 s11, s93, 0
	s_mov_b32 s24, 1
	s_mov_b64 s[14:15], 0
	v_mov_b32_e32 v0, 0
	s_branch .LBB0_1122

; __device__ __forceinline__ int lane_now() { int l; asm volatile("v_mbcnt_lo_u32_b32 %0, -1, 0\n\tv_mbcnt_hi_u32_b32 %0, -1, %0" : "=v"(l)); return l; }
; __device__ __forceinline__ unsigned xb_ld(unsigned* p)              { return __hip_atomic_load(p, __ATOMIC_RELAXED, __HIP_MEMORY_SCOPE_AGENT); }
; __device__ __forceinline__ unsigned xb_add(unsigned* p, unsigned v) { return __hip_atomic_fetch_add(p, v, __ATOMIC_RELAXED, __HIP_MEMORY_SCOPE_AGENT); }
; #define XB_SPIN(cond, bar) do { unsigned _sp = 0; while (cond) { __builtin_amdgcn_s_sleep(1); \
;     if ((++_sp & 255u) == 0u) { if (xb_ld(&(bar)[XB_TMO])) break; if (_sp > XB_SPIN_CAP) { atomicAdd(&(bar)[XB_TMO], 1u); break; } } } } while (0)
; __device__ __forceinline__ void xcd_barrier(const XcdBarrier& b) {
;     asm volatile("s_waitcnt vmcnt(0)" ::: "memory");
;     __syncthreads();
;     if (b.w0 && lane_now() == 0) {
;         unsigned* bar = b.bar;
;         __builtin_amdgcn_s_waitcnt(0);
;         unsigned nloc = b.st[0], nx = b.st[1];
;         if (nloc == 0u) { xcd_barrier_complete(bar, b.x, nloc, nx); b.st[0] = nloc; b.st[1] = nx; }
;         const unsigned old = xb_add(&bar[XB_XSUB(b.x)], 1u);
;         const unsigned gen = old / nloc;
;         if (old + 1u == (gen + 1u) * nloc) {
;             __builtin_amdgcn_fence(__ATOMIC_RELEASE, "agent");
;             asm volatile("s_waitcnt vmcnt(0)" ::: "memory");
;             const unsigned og = xb_add(&bar[XB_TOP], 1u);
;             const unsigned tg = og / nx;
;             if (og + 1u == (tg + 1u) * nx) xb_add(&bar[XB_TOPGEN], 1u);
;             else XB_SPIN(xb_ld(&bar[XB_TOPGEN]) == tg, bar);
;             __builtin_amdgcn_fence(__ATOMIC_ACQUIRE, "agent");
;             xb_add(&bar[XB_XGEN(b.x)], 1u);
;             asm volatile("s_waitcnt vmcnt(0)" ::: "memory");
;         } else {
;             XB_SPIN(xb_ld(&bar[XB_XGEN(b.x)]) == gen, bar);
;             __builtin_amdgcn_fence(__ATOMIC_ACQUIRE, "agent");
;             asm volatile("s_waitcnt vmcnt(0)" ::: "memory");
;         }
;     }
;     __syncthreads();
.LBB0_1151:
	s_or_b64 exec, exec, s[8:9]
	s_waitcnt vmcnt(0)
	s_branch .LBB0_1152

; __device__ __forceinline__ int lane_now() { int l; asm volatile("v_mbcnt_lo_u32_b32 %0, -1, 0\n\tv_mbcnt_hi_u32_b32 %0, -1, %0" : "=v"(l)); return l; }
; __device__ __forceinline__ unsigned xb_ld(unsigned* p)              { return __hip_atomic_load(p, __ATOMIC_RELAXED, __HIP_MEMORY_SCOPE_AGENT); }
; __device__ __forceinline__ unsigned xb_add(unsigned* p, unsigned v) { return __hip_atomic_fetch_add(p, v, __ATOMIC_RELAXED, __HIP_MEMORY_SCOPE_AGENT); }
; #define XB_SPIN(cond, bar) do { unsigned _sp = 0; while (cond) { __builtin_amdgcn_s_sleep(1); \
;     if ((++_sp & 255u) == 0u) { if (xb_ld(&(bar)[XB_TMO])) break; if (_sp > XB_SPIN_CAP) { atomicAdd(&(bar)[XB_TMO], 1u); break; } } } } while (0)
; __device__ __forceinline__ void xcd_barrier(const XcdBarrier& b) {
;     asm volatile("s_waitcnt vmcnt(0)" ::: "memory");
;     __syncthreads();
;     if (b.w0 && lane_now() == 0) {
;         unsigned* bar = b.bar;
;         __builtin_amdgcn_s_waitcnt(0);
;         unsigned nloc = b.st[0], nx = b.st[1];
;         if (nloc == 0u) { xcd_barrier_complete(bar, b.x, nloc, nx); b.st[0] = nloc; b.st[1] = nx; }
;         const unsigned old = xb_add(&bar[XB_XSUB(b.x)], 1u);
;         const unsigned gen = old / nloc;
;         if (old + 1u == (gen + 1u) * nloc) {
;             __builtin_amdgcn_fence(__ATOMIC_RELEASE, "agent");
;             asm volatile("s_waitcnt vmcnt(0)" ::: "memory");
;             const unsigned og = xb_add(&bar[XB_TOP], 1u);
;             const unsigned tg = og / nx;
;             if (og + 1u == (tg + 1u) * nx) xb_add(&bar[XB_TOPGEN], 1u);
;             else XB_SPIN(xb_ld(&bar[XB_TOPGEN]) == tg, bar);
;             __builtin_amdgcn_fence(__ATOMIC_ACQUIRE, "agent");
;             xb_add(&bar[XB_XGEN(b.x)], 1u);
;             asm volatile("s_waitcnt vmcnt(0)" ::: "memory");
;         } else {
;             XB_SPIN(xb_ld(&bar[XB_XGEN(b.x)]) == gen, bar);
;             __builtin_amdgcn_fence(__ATOMIC_ACQUIRE, "agent");
;             asm volatile("s_waitcnt vmcnt(0)" ::: "memory");
;         }
;     }
;     __syncthreads();
.Lel_c11:
	v_readfirstlane_b32 s8, v3
	v_sub_u32_e32 v3, 0, v2
	v_rcp_iflag_f32_e32 v4, v4
	v_add_u32_e32 v5, s8, v1
	v_mul_f32_e32 v4, 0x4f7ffffe, v4
	v_cvt_u32_f32_e32 v4, v4
	v_mul_lo_u32 v1, v3, v4
	v_mul_hi_u32 v1, v4, v1
	v_add_u32_e32 v1, v4, v1
	v_mul_hi_u32 v1, v5, v1
	v_mul_lo_u32 v3, v1, v2
	v_sub_u32_e32 v3, v5, v3
	v_add_u32_e32 v4, 1, v1
	v_cmp_ge_u32_e32 vcc, v3, v2
	s_nop 1
	v_cndmask_b32_e32 v1, v1, v4, vcc
	v_sub_u32_e32 v4, v3, v2
	v_cndmask_b32_e32 v3, v3, v4, vcc
	v_add_u32_e32 v4, 1, v1
	v_cmp_ge_u32_e32 vcc, v3, v2
	v_add_u32_e32 v3, 1, v5
	s_nop 0
	v_cndmask_b32_e32 v1, v1, v4, vcc
	v_mul_lo_u32 v4, v2, v1
	v_add_u32_e32 v2, v4, v2
	v_cmp_ne_u32_e32 vcc, v3, v2
	s_and_saveexec_b64 s[8:9], vcc
	s_xor_b64 s[8:9], exec, s[8:9]
	s_cbranch_execz .LBB0_1281
	s_waitcnt lgkmcnt(0)
	v_mov_b32_e32 v0, 0x2000
	global_load_dword v0, v0, s[6:7] offset:1024 sc1
	s_add_u32 s14, s6, 0x2400
	s_addc_u32 s15, s7, 0
	s_waitcnt vmcnt(0)
	v_cmp_eq_u32_e32 vcc, v0, v1
	s_and_saveexec_b64 s[10:11], vcc
	s_cbranch_execz .LBB0_1280
	s_add_u32 s12, s92, 0xc0200
	s_addc_u32 s13, s93, 0
	s_mov_b32 s26, 1
	s_mov_b64 s[16:17], 0
	v_mov_b32_e32 v0, 0
	s_branch .LBB0_1271

; __device__ __forceinline__ int lane_now() { int l; asm volatile("v_mbcnt_lo_u32_b32 %0, -1, 0\n\tv_mbcnt_hi_u32_b32 %0, -1, %0" : "=v"(l)); return l; }
; __device__ __forceinline__ unsigned xb_ld(unsigned* p)              { return __hip_atomic_load(p, __ATOMIC_RELAXED, __HIP_MEMORY_SCOPE_AGENT); }
; __device__ __forceinline__ unsigned xb_add(unsigned* p, unsigned v) { return __hip_atomic_fetch_add(p, v, __ATOMIC_RELAXED, __HIP_MEMORY_SCOPE_AGENT); }
; #define XB_SPIN(cond, bar) do { unsigned _sp = 0; while (cond) { __builtin_amdgcn_s_sleep(1); \
;     if ((++_sp & 255u) == 0u) { if (xb_ld(&(bar)[XB_TMO])) break; if (_sp > XB_SPIN_CAP) { atomicAdd(&(bar)[XB_TMO], 1u); break; } } } } while (0)
; __device__ __forceinline__ void xcd_barrier(const XcdBarrier& b) {
;     asm volatile("s_waitcnt vmcnt(0)" ::: "memory");
;     __syncthreads();
;     if (b.w0 && lane_now() == 0) {
;         unsigned* bar = b.bar;
;         __builtin_amdgcn_s_waitcnt(0);
;         unsigned nloc = b.st[0], nx = b.st[1];
;         if (nloc == 0u) { xcd_barrier_complete(bar, b.x, nloc, nx); b.st[0] = nloc; b.st[1] = nx; }
;         const unsigned old = xb_add(&bar[XB_XSUB(b.x)], 1u);
;         const unsigned gen = old / nloc;
;         if (old + 1u == (gen + 1u) * nloc) {
;             __builtin_amdgcn_fence(__ATOMIC_RELEASE, "agent");
;             asm volatile("s_waitcnt vmcnt(0)" ::: "memory");
;             const unsigned og = xb_add(&bar[XB_TOP], 1u);
;             const unsigned tg = og / nx;
;             if (og + 1u == (tg + 1u) * nx) xb_add(&bar[XB_TOPGEN], 1u);
;             else XB_SPIN(xb_ld(&bar[XB_TOPGEN]) == tg, bar);
;             __builtin_amdgcn_fence(__ATOMIC_ACQUIRE, "agent");
;             xb_add(&bar[XB_XGEN(b.x)], 1u);
;             asm volatile("s_waitcnt vmcnt(0)" ::: "memory");
;         } else {
;             XB_SPIN(xb_ld(&bar[XB_XGEN(b.x)]) == gen, bar);
;             __builtin_amdgcn_fence(__ATOMIC_ACQUIRE, "agent");
;             asm volatile("s_waitcnt vmcnt(0)" ::: "memory");
;         }
;     }
;     __syncthreads();
.Lel_c12:
	v_readfirstlane_b32 s6, v3
	v_sub_u32_e32 v3, 0, v2
	v_rcp_iflag_f32_e32 v4, v4
	v_add_u32_e32 v5, s6, v1
	v_mul_f32_e32 v4, 0x4f7ffffe, v4
	v_cvt_u32_f32_e32 v4, v4
	v_mul_lo_u32 v1, v3, v4
	v_mul_hi_u32 v1, v4, v1
	v_add_u32_e32 v1, v4, v1
	v_mul_hi_u32 v1, v5, v1
	v_mul_lo_u32 v3, v1, v2
	v_sub_u32_e32 v3, v5, v3
	v_add_u32_e32 v4, 1, v1
	v_cmp_ge_u32_e32 vcc, v3, v2
	s_nop 1
	v_cndmask_b32_e32 v1, v1, v4, vcc
	v_sub_u32_e32 v4, v3, v2
	v_cndmask_b32_e32 v3, v3, v4, vcc
	v_add_u32_e32 v4, 1, v1
	v_cmp_ge_u32_e32 vcc, v3, v2
	v_add_u32_e32 v3, 1, v5
	s_nop 0
	v_cndmask_b32_e32 v1, v1, v4, vcc
	v_mul_lo_u32 v4, v2, v1
	v_add_u32_e32 v2, v4, v2
	v_cmp_ne_u32_e32 vcc, v3, v2
	s_and_saveexec_b64 s[6:7], vcc
	s_xor_b64 s[6:7], exec, s[6:7]
	s_cbranch_execz .LBB0_1351
	s_waitcnt lgkmcnt(0)
	v_mov_b32_e32 v0, 0x2000
	global_load_dword v0, v0, s[2:3] offset:1024 sc1
	s_add_u32 s12, s2, 0x2400
	s_addc_u32 s13, s3, 0
	s_waitcnt vmcnt(0)
	v_cmp_eq_u32_e32 vcc, v0, v1
	s_and_saveexec_b64 s[8:9], vcc
	s_cbranch_execz .LBB0_1350
	s_add_u32 s10, s92, 0xc0200
	s_addc_u32 s11, s93, 0
	s_mov_b32 s24, 1
	s_mov_b64 s[14:15], 0
	v_mov_b32_e32 v0, 0
	s_branch .LBB0_1341

; __device__ __forceinline__ int lane_now() { int l; asm volatile("v_mbcnt_lo_u32_b32 %0, -1, 0\n\tv_mbcnt_hi_u32_b32 %0, -1, %0" : "=v"(l)); return l; }
; __device__ __forceinline__ unsigned xb_ld(unsigned* p)              { return __hip_atomic_load(p, __ATOMIC_RELAXED, __HIP_MEMORY_SCOPE_AGENT); }
; __device__ __forceinline__ unsigned xb_add(unsigned* p, unsigned v) { return __hip_atomic_fetch_add(p, v, __ATOMIC_RELAXED, __HIP_MEMORY_SCOPE_AGENT); }
; #define XB_SPIN(cond, bar) do { unsigned _sp = 0; while (cond) { __builtin_amdgcn_s_sleep(1); \
;     if ((++_sp & 255u) == 0u) { if (xb_ld(&(bar)[XB_TMO])) break; if (_sp > XB_SPIN_CAP) { atomicAdd(&(bar)[XB_TMO], 1u); break; } } } } while (0)
; __device__ __forceinline__ void xcd_barrier(const XcdBarrier& b) {
;     asm volatile("s_waitcnt vmcnt(0)" ::: "memory");
;     __syncthreads();
;     if (b.w0 && lane_now() == 0) {
;         unsigned* bar = b.bar;
;         __builtin_amdgcn_s_waitcnt(0);
;         unsigned nloc = b.st[0], nx = b.st[1];
;         if (nloc == 0u) { xcd_barrier_complete(bar, b.x, nloc, nx); b.st[0] = nloc; b.st[1] = nx; }
;         const unsigned old = xb_add(&bar[XB_XSUB(b.x)], 1u);
;         const unsigned gen = old / nloc;
;         if (old + 1u == (gen + 1u) * nloc) {
;             __builtin_amdgcn_fence(__ATOMIC_RELEASE, "agent");
;             asm volatile("s_waitcnt vmcnt(0)" ::: "memory");
;             const unsigned og = xb_add(&bar[XB_TOP], 1u);
;             const unsigned tg = og / nx;
;             if (og + 1u == (tg + 1u) * nx) xb_add(&bar[XB_TOPGEN], 1u);
;             else XB_SPIN(xb_ld(&bar[XB_TOPGEN]) == tg, bar);
;             __builtin_amdgcn_fence(__ATOMIC_ACQUIRE, "agent");
;             xb_add(&bar[XB_XGEN(b.x)], 1u);
;             asm volatile("s_waitcnt vmcnt(0)" ::: "memory");
;         } else {
;             XB_SPIN(xb_ld(&bar[XB_XGEN(b.x)]) == gen, bar);
;             __builtin_amdgcn_fence(__ATOMIC_ACQUIRE, "agent");
;             asm volatile("s_waitcnt vmcnt(0)" ::: "memory");
;         }
;     }
;     __syncthreads();
.Lel_rel12:
	v_mov_b32_e32 v0, 0x2000
	v_mov_b32_e32 v1, 1
	global_atomic_add v0, v1, s[2:3] offset:1024
	s_waitcnt vmcnt(0)
	s_branch .LBB0_1371
